# P0 weight conversion: the 16 per-row norm-gain loads of the scaled variants (w_in, gate, up) issued together and waited once instead of 8 serialised pairs
# speedup vs baseline: 1.0024x; 1.0006x over previous
; #define LAS __attribute__((address_space(3)))
; __device__ __forceinline__ void conv_item(const float* __restrict__ W, int K, int N, bf16* WT, const float* __restrict__ g, int mode, LAS float* scr, int item, int lane) {
;     const int nblk = N / 64, kb = item / nblk, nb = item % nblk, k0 = 64 * kb, n0 = 64 * nb;
;     f32x4 v[16];
; #pragma unroll
;     for (int i = 0; i < 16; ++i) v[i] = __builtin_nontemporal_load((const f32x4*)(W + (size_t)(k0 + 4 * i + (lane >> 4)) * N + n0 + 4 * (lane & 15)));
; #pragma unroll
;     for (int i = 0; i < 16; ++i) { const int kk = 4 * i + (lane >> 4); const float sc = g ? g[k0 + kk] : 1.f; LAS float* d = scr + kk * 65 + 4 * (lane & 15);
;         d[0] = v[i][0] * sc; d[1] = v[i][1] * sc; d[2] = v[i][2] * sc; d[3] = v[i][3] * sc; }
.LBB0_58:
	s_andn2_b64 vcc, exec, s[2:3]
	s_cbranch_vccnz .LBB0_84
	s_add_i32 s0, s59, 0xe800
	s_and_b32 s2, s0, 0xffff
	s_mul_i32 s2, s2, 0xba2f
	s_lshr_b32 s3, s2, 16
	s_lshr_b32 s2, s2, 22
	s_mulk_i32 s2, 0x58
	s_sub_i32 s31, s0, s2
	s_and_b32 s30, s3, 0xffc0
	v_or_b32_e32 v95, s30, v68
	s_lshl_b32 s0, s31, 8
	s_and_b32 s0, s0, 0x3ff00
	v_mul_u32_u24_e32 v4, 0x1600, v95
	v_lshl_add_u64 v[0:1], v[76:77], 0, s[0:1]
	v_lshlrev_b32_e32 v70, 2, v4
	v_mad_u64_u32 v[2:3], s[2:3], v95, s45, v[0:1]
	v_lshl_add_u64 v[0:1], v[0:1], 0, v[70:71]
	v_add_co_u32_e32 v4, vcc, s46, v0
	v_cndmask_b32_e64 v70, 0, 1, s[6:7]
	s_nop 0
	v_addc_co_u32_e32 v5, vcc, 0, v1, vcc
	global_load_dwordx4 v[60:63], v[2:3], off nt
	global_load_dwordx4 v[56:59], v[4:5], off nt
	v_add_co_u32_e32 v2, vcc, s47, v0
	v_cmp_ne_u32_e64 s[4:5], 1, v70
	s_nop 0
	v_addc_co_u32_e32 v3, vcc, 0, v1, vcc
	v_add_co_u32_e32 v4, vcc, s48, v0
	v_add_lshl_u32 v94, v68, s30, 2
	s_nop 0
	v_addc_co_u32_e32 v5, vcc, 0, v1, vcc
	global_load_dwordx4 v[52:55], v[2:3], off nt
	global_load_dwordx4 v[48:51], v[4:5], off nt
	v_add_co_u32_e32 v2, vcc, s44, v0
	s_nop 1
	v_addc_co_u32_e32 v3, vcc, 0, v1, vcc
	v_add_co_u32_e32 v4, vcc, s49, v0
	s_nop 1
	v_addc_co_u32_e32 v5, vcc, 0, v1, vcc
	global_load_dwordx4 v[44:47], v[2:3], off nt
	global_load_dwordx4 v[40:43], v[4:5], off nt
	v_add_co_u32_e32 v2, vcc, s50, v0
	s_nop 1
	v_addc_co_u32_e32 v3, vcc, 0, v1, vcc
	v_add_co_u32_e32 v4, vcc, s51, v0
	s_nop 1
	v_addc_co_u32_e32 v5, vcc, 0, v1, vcc
	global_load_dwordx4 v[36:39], v[2:3], off nt
	global_load_dwordx4 v[32:35], v[4:5], off nt
	v_add_co_u32_e32 v2, vcc, s52, v0
	s_nop 1
	v_addc_co_u32_e32 v3, vcc, 0, v1, vcc
	v_add_co_u32_e32 v4, vcc, s53, v0
	s_nop 1
	v_addc_co_u32_e32 v5, vcc, 0, v1, vcc
	global_load_dwordx4 v[28:31], v[2:3], off nt
	global_load_dwordx4 v[24:27], v[4:5], off nt
	v_add_co_u32_e32 v2, vcc, s54, v0
	s_nop 1
	v_addc_co_u32_e32 v3, vcc, 0, v1, vcc
	v_add_co_u32_e32 v4, vcc, s55, v0
	s_nop 1
	v_addc_co_u32_e32 v5, vcc, 0, v1, vcc
	global_load_dwordx4 v[20:23], v[2:3], off nt
	global_load_dwordx4 v[16:19], v[4:5], off nt
	v_add_co_u32_e32 v2, vcc, s56, v0
	s_nop 1
	v_addc_co_u32_e32 v3, vcc, 0, v1, vcc
	v_add_co_u32_e32 v4, vcc, 0x11e000, v0
	s_nop 1
	v_addc_co_u32_e32 v5, vcc, 0, v1, vcc
	global_load_dwordx4 v[12:15], v[2:3], off nt
	global_load_dwordx4 v[8:11], v[4:5], off nt
	v_add_co_u32_e32 v2, vcc, 0x134000, v0
	s_nop 1
	v_addc_co_u32_e32 v3, vcc, 0, v1, vcc
	v_add_co_u32_e32 v0, vcc, 0x14a000, v0
	s_nop 1
	v_addc_co_u32_e32 v1, vcc, 0, v1, vcc
	global_load_dwordx4 v[4:7], v[2:3], off nt
	s_nop 0
	global_load_dwordx4 v[0:3], v[0:1], off nt
	s_andn2_b64 vcc, exec, s[6:7]
	s_cbranch_vccnz .LBB0_158
	v_lshlrev_b32_e32 v70, 2, v95
	global_load_dword v134, v70, s[84:85]
	global_load_dword v135, v94, s[84:85] offset:16
	global_load_dword v136, v94, s[84:85] offset:32
	global_load_dword v137, v94, s[84:85] offset:48
	global_load_dword v138, v94, s[84:85] offset:64
	global_load_dword v139, v94, s[84:85] offset:80
	global_load_dword v140, v94, s[84:85] offset:96
	global_load_dword v141, v94, s[84:85] offset:112
	global_load_dword v142, v94, s[84:85] offset:128
	global_load_dword v143, v94, s[84:85] offset:144
	global_load_dword v144, v94, s[84:85] offset:160
	global_load_dword v145, v94, s[84:85] offset:176
	global_load_dword v146, v94, s[84:85] offset:192
	global_load_dword v147, v94, s[84:85] offset:208
	global_load_dword v148, v94, s[84:85] offset:224
	global_load_dword v149, v94, s[84:85] offset:240
	s_waitcnt vmcnt(0)
	v_mov_b32_e32 v124, v134
	v_mov_b32_e32 v70, v135
	s_waitcnt vmcnt(1)
	v_pk_mul_f32 v[126:127], v[60:61], v[124:125] op_sel_hi:[1,0]
	v_pk_mul_f32 v[124:125], v[62:63], v[124:125] op_sel_hi:[1,0]
	ds_write2_b32 v67, v126, v127 offset1:1
	ds_write2_b32 v67, v124, v125 offset0:2 offset1:3
	s_cbranch_execnz .LBB0_62

; #define LAS __attribute__((address_space(3)))
; __device__ __forceinline__ void conv_item(const float* __restrict__ W, int K, int N, bf16* WT, const float* __restrict__ g, int mode, LAS float* scr, int item, int lane) {
;     ...
; #pragma unroll
;     for (int i = 0; i < 16; ++i) { const int kk = 4 * i + (lane >> 4); const float sc = g ? g[k0 + kk] : 1.f; LAS float* d = scr + kk * 65 + 4 * (lane & 15);
;         d[0] = v[i][0] * sc; d[1] = v[i][1] * sc; d[2] = v[i][2] * sc; d[3] = v[i][3] * sc; }
.LBB0_62:
	s_waitcnt vmcnt(0)
	v_pk_mul_f32 v[56:57], v[56:57], v[70:71] op_sel_hi:[1,0]
	v_add_u32_e32 v60, v65, v106
	ds_write2_b32 v60, v56, v57 offset1:1
	v_pk_mul_f32 v[56:57], v[58:59], v[70:71] op_sel_hi:[1,0]
	s_and_b64 vcc, exec, s[4:5]
	ds_write2_b32 v60, v56, v57 offset0:2 offset1:3
	s_cbranch_vccnz .LBB0_159
	v_mov_b32_e32 v58, v136
	v_mov_b32_e32 v56, v137
	v_add_u32_e32 v57, v65, v107
	s_waitcnt vmcnt(1)
	v_pk_mul_f32 v[60:61], v[52:53], v[58:59] op_sel_hi:[1,0]
	v_pk_mul_f32 v[58:59], v[54:55], v[58:59] op_sel_hi:[1,0]
	ds_write2_b32 v57, v60, v61 offset1:1
	ds_write2_b32 v57, v58, v59 offset0:2 offset1:3
	s_cbranch_execnz .LBB0_65

; #define LAS __attribute__((address_space(3)))
; __device__ __forceinline__ void conv_item(const float* __restrict__ W, int K, int N, bf16* WT, const float* __restrict__ g, int mode, LAS float* scr, int item, int lane) {
;     ...
; #pragma unroll
;     for (int i = 0; i < 16; ++i) { const int kk = 4 * i + (lane >> 4); const float sc = g ? g[k0 + kk] : 1.f; LAS float* d = scr + kk * 65 + 4 * (lane & 15);
;         d[0] = v[i][0] * sc; d[1] = v[i][1] * sc; d[2] = v[i][2] * sc; d[3] = v[i][3] * sc; }
.LBB0_65:
	s_waitcnt vmcnt(0)
	v_pk_mul_f32 v[48:49], v[48:49], v[56:57] op_sel_hi:[1,0]
	v_add_u32_e32 v52, v65, v108
	ds_write2_b32 v52, v48, v49 offset1:1
	v_pk_mul_f32 v[48:49], v[50:51], v[56:57] op_sel_hi:[1,0]
	s_and_b64 vcc, exec, s[4:5]
	ds_write2_b32 v52, v48, v49 offset0:2 offset1:3
	s_cbranch_vccnz .LBB0_160
	v_mov_b32_e32 v50, v138
	v_mov_b32_e32 v48, v139
	v_add_u32_e32 v49, v65, v109
	s_waitcnt vmcnt(1)
	v_pk_mul_f32 v[52:53], v[44:45], v[50:51] op_sel_hi:[1,0]
	v_pk_mul_f32 v[50:51], v[46:47], v[50:51] op_sel_hi:[1,0]
	ds_write2_b32 v49, v52, v53 offset1:1
	ds_write2_b32 v49, v50, v51 offset0:2 offset1:3
	s_cbranch_execnz .LBB0_68

; #define LAS __attribute__((address_space(3)))
; __device__ __forceinline__ void conv_item(const float* __restrict__ W, int K, int N, bf16* WT, const float* __restrict__ g, int mode, LAS float* scr, int item, int lane) {
;     ...
; #pragma unroll
;     for (int i = 0; i < 16; ++i) { const int kk = 4 * i + (lane >> 4); const float sc = g ? g[k0 + kk] : 1.f; LAS float* d = scr + kk * 65 + 4 * (lane & 15);
;         d[0] = v[i][0] * sc; d[1] = v[i][1] * sc; d[2] = v[i][2] * sc; d[3] = v[i][3] * sc; }
.LBB0_68:
	s_waitcnt vmcnt(0)
	v_pk_mul_f32 v[40:41], v[40:41], v[48:49] op_sel_hi:[1,0]
	v_add_u32_e32 v44, v65, v110
	ds_write2_b32 v44, v40, v41 offset1:1
	v_pk_mul_f32 v[40:41], v[42:43], v[48:49] op_sel_hi:[1,0]
	s_and_b64 vcc, exec, s[4:5]
	ds_write2_b32 v44, v40, v41 offset0:2 offset1:3
	s_cbranch_vccnz .LBB0_161
	v_mov_b32_e32 v42, v140
	v_mov_b32_e32 v40, v141
	v_add_u32_e32 v41, v65, v111
	s_waitcnt vmcnt(1)
	v_pk_mul_f32 v[44:45], v[36:37], v[42:43] op_sel_hi:[1,0]
	v_pk_mul_f32 v[42:43], v[38:39], v[42:43] op_sel_hi:[1,0]
	ds_write2_b32 v41, v44, v45 offset1:1
	ds_write2_b32 v41, v42, v43 offset0:2 offset1:3
	s_cbranch_execnz .LBB0_71

; #define LAS __attribute__((address_space(3)))
; __device__ __forceinline__ void conv_item(const float* __restrict__ W, int K, int N, bf16* WT, const float* __restrict__ g, int mode, LAS float* scr, int item, int lane) {
;     ...
; #pragma unroll
;     for (int i = 0; i < 16; ++i) { const int kk = 4 * i + (lane >> 4); const float sc = g ? g[k0 + kk] : 1.f; LAS float* d = scr + kk * 65 + 4 * (lane & 15);
;         d[0] = v[i][0] * sc; d[1] = v[i][1] * sc; d[2] = v[i][2] * sc; d[3] = v[i][3] * sc; }
.LBB0_71:
	s_waitcnt vmcnt(0)
	v_pk_mul_f32 v[32:33], v[32:33], v[40:41] op_sel_hi:[1,0]
	v_add_u32_e32 v36, v65, v112
	ds_write2_b32 v36, v32, v33 offset1:1
	v_pk_mul_f32 v[32:33], v[34:35], v[40:41] op_sel_hi:[1,0]
	s_and_b64 vcc, exec, s[4:5]
	ds_write2_b32 v36, v32, v33 offset0:2 offset1:3
	s_cbranch_vccnz .LBB0_162
	v_mov_b32_e32 v34, v142
	v_mov_b32_e32 v32, v143
	v_add_u32_e32 v33, v65, v113
	s_waitcnt vmcnt(1)
	v_pk_mul_f32 v[36:37], v[28:29], v[34:35] op_sel_hi:[1,0]
	v_pk_mul_f32 v[34:35], v[30:31], v[34:35] op_sel_hi:[1,0]
	ds_write2_b32 v33, v36, v37 offset1:1
	ds_write2_b32 v33, v34, v35 offset0:2 offset1:3
	s_cbranch_execnz .LBB0_74

; #define LAS __attribute__((address_space(3)))
; __device__ __forceinline__ void conv_item(const float* __restrict__ W, int K, int N, bf16* WT, const float* __restrict__ g, int mode, LAS float* scr, int item, int lane) {
;     ...
; #pragma unroll
;     for (int i = 0; i < 16; ++i) { const int kk = 4 * i + (lane >> 4); const float sc = g ? g[k0 + kk] : 1.f; LAS float* d = scr + kk * 65 + 4 * (lane & 15);
;         d[0] = v[i][0] * sc; d[1] = v[i][1] * sc; d[2] = v[i][2] * sc; d[3] = v[i][3] * sc; }
.LBB0_74:
	s_waitcnt vmcnt(0)
	v_pk_mul_f32 v[24:25], v[24:25], v[32:33] op_sel_hi:[1,0]
	v_add_u32_e32 v28, v65, v114
	ds_write2_b32 v28, v24, v25 offset1:1
	v_pk_mul_f32 v[24:25], v[26:27], v[32:33] op_sel_hi:[1,0]
	s_and_b64 vcc, exec, s[4:5]
	ds_write2_b32 v28, v24, v25 offset0:2 offset1:3
	s_cbranch_vccnz .LBB0_163
	v_mov_b32_e32 v26, v144
	v_mov_b32_e32 v24, v145
	v_add_u32_e32 v25, v65, v115
	s_waitcnt vmcnt(1)
	v_pk_mul_f32 v[28:29], v[20:21], v[26:27] op_sel_hi:[1,0]
	v_pk_mul_f32 v[26:27], v[22:23], v[26:27] op_sel_hi:[1,0]
	ds_write2_b32 v25, v28, v29 offset1:1
	ds_write2_b32 v25, v26, v27 offset0:2 offset1:3
	s_cbranch_execnz .LBB0_77

; #define LAS __attribute__((address_space(3)))
; __device__ __forceinline__ void conv_item(const float* __restrict__ W, int K, int N, bf16* WT, const float* __restrict__ g, int mode, LAS float* scr, int item, int lane) {
;     ...
; #pragma unroll
;     for (int i = 0; i < 16; ++i) { const int kk = 4 * i + (lane >> 4); const float sc = g ? g[k0 + kk] : 1.f; LAS float* d = scr + kk * 65 + 4 * (lane & 15);
;         d[0] = v[i][0] * sc; d[1] = v[i][1] * sc; d[2] = v[i][2] * sc; d[3] = v[i][3] * sc; }
.LBB0_77:
	s_waitcnt vmcnt(0)
	v_pk_mul_f32 v[20:21], v[16:17], v[24:25] op_sel_hi:[1,0]
	v_add_u32_e32 v17, v65, v116
	v_pk_mul_f32 v[18:19], v[18:19], v[24:25] op_sel_hi:[1,0]
	ds_write2_b32 v17, v18, v19 offset0:2 offset1:3
	s_and_b64 vcc, exec, s[4:5]
	v_add_u32_e32 v18, 0x410, v17
	v_add_u32_e32 v19, 0x418, v17
	ds_write2_b32 v17, v20, v21 offset1:1
	s_cbranch_vccnz .LBB0_164
	v_mov_b32_e32 v20, v146
	v_mov_b32_e32 v16, v147
	s_waitcnt vmcnt(1)
	v_pk_mul_f32 v[22:23], v[12:13], v[20:21] op_sel_hi:[1,0]
	v_pk_mul_f32 v[20:21], v[14:15], v[20:21] op_sel_hi:[1,0]
	ds_write2_b32 v18, v22, v23 offset1:1
	ds_write2_b32 v19, v20, v21 offset1:1
	s_cbranch_execnz .LBB0_80

; #define LAS __attribute__((address_space(3)))
; __device__ __forceinline__ void conv_item(const float* __restrict__ W, int K, int N, bf16* WT, const float* __restrict__ g, int mode, LAS float* scr, int item, int lane) {
;     ...
; #pragma unroll
;     for (int i = 0; i < 16; ++i) { const int kk = 4 * i + (lane >> 4); const float sc = g ? g[k0 + kk] : 1.f; LAS float* d = scr + kk * 65 + 4 * (lane & 15);
;         d[0] = v[i][0] * sc; d[1] = v[i][1] * sc; d[2] = v[i][2] * sc; d[3] = v[i][3] * sc; }
.LBB0_80:
	s_waitcnt vmcnt(0)
	v_pk_mul_f32 v[8:9], v[8:9], v[16:17] op_sel_hi:[1,0]
	v_add_u32_e32 v12, 0x820, v17
	ds_write2_b32 v12, v8, v9 offset1:1
	v_pk_mul_f32 v[8:9], v[10:11], v[16:17] op_sel_hi:[1,0]
	v_add_u32_e32 v10, 0x828, v17
	ds_write2_b32 v10, v8, v9 offset1:1
	s_and_b64 vcc, exec, s[4:5]
	v_add_u32_e32 v9, 0xc30, v17
	v_add_u32_e32 v10, 0xc38, v17
	s_cbranch_vccnz .LBB0_165
	v_mov_b32_e32 v12, v148
	v_mov_b32_e32 v8, v149
	s_waitcnt vmcnt(1)
	v_pk_mul_f32 v[14:15], v[4:5], v[12:13] op_sel_hi:[1,0]
	v_pk_mul_f32 v[12:13], v[6:7], v[12:13] op_sel_hi:[1,0]
	ds_write2_b32 v9, v14, v15 offset1:1
	ds_write2_b32 v10, v12, v13 offset1:1
	s_cbranch_execnz .LBB0_83

; #define LAS __attribute__((address_space(3)))
; __device__ __forceinline__ void conv_item(const float* __restrict__ W, int K, int N, bf16* WT, const float* __restrict__ g, int mode, LAS float* scr, int item, int lane) {
;     const int nblk = N / 64, kb = item / nblk, nb = item % nblk, k0 = 64 * kb, n0 = 64 * nb;
;     f32x4 v[16];
; #pragma unroll
;     for (int i = 0; i < 16; ++i) v[i] = __builtin_nontemporal_load((const f32x4*)(W + (size_t)(k0 + 4 * i + (lane >> 4)) * N + n0 + 4 * (lane & 15)));
; #pragma unroll
;     for (int i = 0; i < 16; ++i) { const int kk = 4 * i + (lane >> 4); const float sc = g ? g[k0 + kk] : 1.f; LAS float* d = scr + kk * 65 + 4 * (lane & 15);
;         d[0] = v[i][0] * sc; d[1] = v[i][1] * sc; d[2] = v[i][2] * sc; d[3] = v[i][3] * sc; }
.LBB0_85:
	s_andn2_b64 vcc, exec, s[2:3]
	s_cbranch_vccnz .LBB0_111
	s_add_i32 s0, s59, 0xf300
	s_and_b32 s2, s0, 0xffff
	s_mul_i32 s2, s2, 0xba2f
	s_lshr_b32 s3, s2, 16
	s_lshr_b32 s2, s2, 22
	s_mulk_i32 s2, 0x58
	s_sub_i32 s31, s0, s2
	s_and_b32 s30, s3, 0xffc0
	v_or_b32_e32 v95, s30, v68
	s_lshl_b32 s0, s31, 8
	s_and_b32 s0, s0, 0x3ff00
	v_mul_u32_u24_e32 v4, 0x1600, v95
	v_lshl_add_u64 v[0:1], v[80:81], 0, s[0:1]
	v_lshlrev_b32_e32 v70, 2, v4
	v_mad_u64_u32 v[2:3], s[2:3], v95, s45, v[0:1]
	v_lshl_add_u64 v[0:1], v[0:1], 0, v[70:71]
	v_add_co_u32_e32 v4, vcc, s46, v0
	v_cndmask_b32_e64 v70, 0, 1, s[6:7]
	s_nop 0
	v_addc_co_u32_e32 v5, vcc, 0, v1, vcc
	global_load_dwordx4 v[60:63], v[2:3], off nt
	global_load_dwordx4 v[56:59], v[4:5], off nt
	v_add_co_u32_e32 v2, vcc, s47, v0
	v_cmp_ne_u32_e64 s[4:5], 1, v70
	s_nop 0
	v_addc_co_u32_e32 v3, vcc, 0, v1, vcc
	v_add_co_u32_e32 v4, vcc, s48, v0
	v_add_lshl_u32 v94, v68, s30, 2
	s_nop 0
	v_addc_co_u32_e32 v5, vcc, 0, v1, vcc
	global_load_dwordx4 v[52:55], v[2:3], off nt
	global_load_dwordx4 v[48:51], v[4:5], off nt
	v_add_co_u32_e32 v2, vcc, s44, v0
	s_nop 1
	v_addc_co_u32_e32 v3, vcc, 0, v1, vcc
	v_add_co_u32_e32 v4, vcc, s49, v0
	s_nop 1
	v_addc_co_u32_e32 v5, vcc, 0, v1, vcc
	global_load_dwordx4 v[44:47], v[2:3], off nt
	global_load_dwordx4 v[40:43], v[4:5], off nt
	v_add_co_u32_e32 v2, vcc, s50, v0
	s_nop 1
	v_addc_co_u32_e32 v3, vcc, 0, v1, vcc
	v_add_co_u32_e32 v4, vcc, s51, v0
	s_nop 1
	v_addc_co_u32_e32 v5, vcc, 0, v1, vcc
	global_load_dwordx4 v[36:39], v[2:3], off nt
	global_load_dwordx4 v[32:35], v[4:5], off nt
	v_add_co_u32_e32 v2, vcc, s52, v0
	s_nop 1
	v_addc_co_u32_e32 v3, vcc, 0, v1, vcc
	v_add_co_u32_e32 v4, vcc, s53, v0
	s_nop 1
	v_addc_co_u32_e32 v5, vcc, 0, v1, vcc
	global_load_dwordx4 v[28:31], v[2:3], off nt
	global_load_dwordx4 v[24:27], v[4:5], off nt
	v_add_co_u32_e32 v2, vcc, s54, v0
	s_nop 1
	v_addc_co_u32_e32 v3, vcc, 0, v1, vcc
	v_add_co_u32_e32 v4, vcc, s55, v0
	s_nop 1
	v_addc_co_u32_e32 v5, vcc, 0, v1, vcc
	global_load_dwordx4 v[20:23], v[2:3], off nt
	global_load_dwordx4 v[16:19], v[4:5], off nt
	v_add_co_u32_e32 v2, vcc, s56, v0
	s_nop 1
	v_addc_co_u32_e32 v3, vcc, 0, v1, vcc
	v_add_co_u32_e32 v4, vcc, 0x11e000, v0
	s_nop 1
	v_addc_co_u32_e32 v5, vcc, 0, v1, vcc
	global_load_dwordx4 v[12:15], v[2:3], off nt
	global_load_dwordx4 v[8:11], v[4:5], off nt
	v_add_co_u32_e32 v2, vcc, 0x134000, v0
	s_nop 1
	v_addc_co_u32_e32 v3, vcc, 0, v1, vcc
	v_add_co_u32_e32 v0, vcc, 0x14a000, v0
	s_nop 1
	v_addc_co_u32_e32 v1, vcc, 0, v1, vcc
	global_load_dwordx4 v[4:7], v[2:3], off nt
	s_nop 0
	global_load_dwordx4 v[0:3], v[0:1], off nt
	s_andn2_b64 vcc, exec, s[6:7]
	s_cbranch_vccnz .LBB0_150
	v_lshlrev_b32_e32 v70, 2, v95
	global_load_dword v134, v70, s[84:85]
	global_load_dword v135, v94, s[84:85] offset:16
	global_load_dword v136, v94, s[84:85] offset:32
	global_load_dword v137, v94, s[84:85] offset:48
	global_load_dword v138, v94, s[84:85] offset:64
	global_load_dword v139, v94, s[84:85] offset:80
	global_load_dword v140, v94, s[84:85] offset:96
	global_load_dword v141, v94, s[84:85] offset:112
	global_load_dword v142, v94, s[84:85] offset:128
	global_load_dword v143, v94, s[84:85] offset:144
	global_load_dword v144, v94, s[84:85] offset:160
	global_load_dword v145, v94, s[84:85] offset:176
	global_load_dword v146, v94, s[84:85] offset:192
	global_load_dword v147, v94, s[84:85] offset:208
	global_load_dword v148, v94, s[84:85] offset:224
	global_load_dword v149, v94, s[84:85] offset:240
	s_waitcnt vmcnt(0)
	v_mov_b32_e32 v124, v134
	v_mov_b32_e32 v70, v135
	s_waitcnt vmcnt(1)
	v_pk_mul_f32 v[126:127], v[60:61], v[124:125] op_sel_hi:[1,0]
	v_pk_mul_f32 v[124:125], v[62:63], v[124:125] op_sel_hi:[1,0]
	ds_write2_b32 v67, v126, v127 offset1:1
	ds_write2_b32 v67, v124, v125 offset0:2 offset1:3
	s_cbranch_execnz .LBB0_89

; #define LAS __attribute__((address_space(3)))
; __device__ __forceinline__ void conv_item(const float* __restrict__ W, int K, int N, bf16* WT, const float* __restrict__ g, int mode, LAS float* scr, int item, int lane) {
;     const int nblk = N / 64, kb = item / nblk, nb = item % nblk, k0 = 64 * kb, n0 = 64 * nb;
;     f32x4 v[16];
; #pragma unroll
;     for (int i = 0; i < 16; ++i) v[i] = __builtin_nontemporal_load((const f32x4*)(W + (size_t)(k0 + 4 * i + (lane >> 4)) * N + n0 + 4 * (lane & 15)));
; #pragma unroll
;     for (int i = 0; i < 16; ++i) { const int kk = 4 * i + (lane >> 4); const float sc = g ? g[k0 + kk] : 1.f; LAS float* d = scr + kk * 65 + 4 * (lane & 15);
;         d[0] = v[i][0] * sc; d[1] = v[i][1] * sc; d[2] = v[i][2] * sc; d[3] = v[i][3] * sc; }
.LBB0_118:
	s_andn2_b64 vcc, exec, s[2:3]
	s_cbranch_vccnz .LBB0_51
	s_ashr_i32 s0, s59, 31
	s_lshr_b32 s0, s0, 26
	s_add_i32 s0, s59, s0
	s_ashr_i32 s3, s0, 6
	s_and_b32 s2, s0, 0xffffffc0
	s_lshl_b32 s0, s3, 12
	v_or_b32_e32 v94, s2, v68
	s_sub_i32 s30, s37, s0
	v_or_b32_e32 v4, 4, v94
	s_ashr_i32 s31, s30, 31
	v_ashrrev_i32_e32 v95, 31, v94
	v_ashrrev_i32_e32 v5, 31, v4
	v_lshl_add_u64 v[0:1], s[30:31], 2, v[90:91]
	v_lshlrev_b64 v[2:3], 14, v[94:95]
	v_lshlrev_b64 v[4:5], 14, v[4:5]
	v_lshl_add_u64 v[2:3], v[0:1], 0, v[2:3]
	v_lshl_add_u64 v[4:5], v[0:1], 0, v[4:5]
	global_load_dwordx4 v[60:63], v[2:3], off nt
	global_load_dwordx4 v[56:59], v[4:5], off nt
	v_or_b32_e32 v2, 8, v94
	v_or_b32_e32 v4, 12, v94
	v_ashrrev_i32_e32 v3, 31, v2
	v_ashrrev_i32_e32 v5, 31, v4
	v_lshlrev_b64 v[2:3], 14, v[2:3]
	v_lshlrev_b64 v[4:5], 14, v[4:5]
	v_lshl_add_u64 v[2:3], v[0:1], 0, v[2:3]
	v_lshl_add_u64 v[4:5], v[0:1], 0, v[4:5]
	global_load_dwordx4 v[52:55], v[2:3], off nt
	global_load_dwordx4 v[48:51], v[4:5], off nt
	v_or_b32_e32 v2, 16, v94
	v_or_b32_e32 v4, 20, v94
	v_ashrrev_i32_e32 v3, 31, v2
	v_ashrrev_i32_e32 v5, 31, v4
	v_lshlrev_b64 v[2:3], 14, v[2:3]
	v_lshlrev_b64 v[4:5], 14, v[4:5]
	v_lshl_add_u64 v[2:3], v[0:1], 0, v[2:3]
	v_lshl_add_u64 v[4:5], v[0:1], 0, v[4:5]
	global_load_dwordx4 v[44:47], v[2:3], off nt
	global_load_dwordx4 v[40:43], v[4:5], off nt
	v_or_b32_e32 v2, 24, v94
	v_or_b32_e32 v4, 28, v94
	v_ashrrev_i32_e32 v3, 31, v2
	v_ashrrev_i32_e32 v5, 31, v4
	v_lshlrev_b64 v[2:3], 14, v[2:3]
	v_lshlrev_b64 v[4:5], 14, v[4:5]
	v_lshl_add_u64 v[2:3], v[0:1], 0, v[2:3]
	v_lshl_add_u64 v[4:5], v[0:1], 0, v[4:5]
	global_load_dwordx4 v[36:39], v[2:3], off nt
	global_load_dwordx4 v[32:35], v[4:5], off nt
	v_or_b32_e32 v2, 32, v94
	v_or_b32_e32 v4, 36, v94
	v_ashrrev_i32_e32 v3, 31, v2
	v_ashrrev_i32_e32 v5, 31, v4
	v_lshlrev_b64 v[2:3], 14, v[2:3]
	v_lshlrev_b64 v[4:5], 14, v[4:5]
	v_lshl_add_u64 v[2:3], v[0:1], 0, v[2:3]
	v_lshl_add_u64 v[4:5], v[0:1], 0, v[4:5]
	global_load_dwordx4 v[28:31], v[2:3], off nt
	global_load_dwordx4 v[24:27], v[4:5], off nt
	v_or_b32_e32 v2, 40, v94
	v_or_b32_e32 v4, 44, v94
	v_ashrrev_i32_e32 v3, 31, v2
	v_ashrrev_i32_e32 v5, 31, v4
	v_lshlrev_b64 v[2:3], 14, v[2:3]
	v_lshlrev_b64 v[4:5], 14, v[4:5]
	v_lshl_add_u64 v[2:3], v[0:1], 0, v[2:3]
	v_lshl_add_u64 v[4:5], v[0:1], 0, v[4:5]
	global_load_dwordx4 v[20:23], v[2:3], off nt
	global_load_dwordx4 v[16:19], v[4:5], off nt
	v_or_b32_e32 v2, 48, v94
	v_or_b32_e32 v4, 52, v94
	v_ashrrev_i32_e32 v3, 31, v2
	v_ashrrev_i32_e32 v5, 31, v4
	v_lshlrev_b64 v[2:3], 14, v[2:3]
	v_lshlrev_b64 v[4:5], 14, v[4:5]
	v_lshl_add_u64 v[2:3], v[0:1], 0, v[2:3]
	v_lshl_add_u64 v[4:5], v[0:1], 0, v[4:5]
	global_load_dwordx4 v[12:15], v[2:3], off nt
	global_load_dwordx4 v[8:11], v[4:5], off nt
	v_or_b32_e32 v2, 56, v94
	v_or_b32_e32 v4, 60, v94
	v_ashrrev_i32_e32 v3, 31, v2
	v_ashrrev_i32_e32 v5, 31, v4
	v_lshlrev_b64 v[2:3], 14, v[2:3]
	v_lshlrev_b64 v[4:5], 14, v[4:5]
	v_lshl_add_u64 v[2:3], v[0:1], 0, v[2:3]
	v_lshl_add_u64 v[0:1], v[0:1], 0, v[4:5]
	global_load_dwordx4 v[4:7], v[2:3], off nt
	s_nop 0
	global_load_dwordx4 v[0:3], v[0:1], off nt
	v_cndmask_b32_e64 v70, 0, 1, s[16:17]
	v_cmp_ne_u32_e64 s[4:5], 1, v70
	s_andn2_b64 vcc, exec, s[16:17]
	s_cbranch_vccnz .LBB0_142
	s_ashr_i32 s3, s2, 31
	v_lshl_add_u64 v[94:95], v[94:95], 2, s[14:15]
	v_lshl_add_u64 v[124:125], s[2:3], 0, v[68:69]
	global_load_dword v134, v[94:95], off
	v_lshl_add_u64 v[124:125], v[124:125], 2, s[14:15]
	global_load_dword v135, v[124:125], off offset:16
	global_load_dword v136, v[124:125], off offset:32
	global_load_dword v137, v[124:125], off offset:48
	global_load_dword v138, v[124:125], off offset:64
	global_load_dword v139, v[124:125], off offset:80
	global_load_dword v140, v[124:125], off offset:96
	global_load_dword v141, v[124:125], off offset:112
	global_load_dword v142, v[124:125], off offset:128
	global_load_dword v143, v[124:125], off offset:144
	global_load_dword v144, v[124:125], off offset:160
	global_load_dword v145, v[124:125], off offset:176
	global_load_dword v146, v[124:125], off offset:192
	global_load_dword v147, v[124:125], off offset:208
	global_load_dword v148, v[124:125], off offset:224
	global_load_dword v149, v[124:125], off offset:240
	s_waitcnt vmcnt(0)
	v_mov_b32_e32 v94, v134
	v_mov_b32_e32 v70, v135
	s_waitcnt vmcnt(1)
	v_pk_mul_f32 v[124:125], v[60:61], v[94:95] op_sel_hi:[1,0]
	v_pk_mul_f32 v[94:95], v[62:63], v[94:95] op_sel_hi:[1,0]
	ds_write2_b32 v67, v124, v125 offset1:1
	ds_write2_b32 v67, v94, v95 offset0:2 offset1:3
	s_cbranch_execnz .LBB0_122

; #define LAS __attribute__((address_space(3)))
; __device__ __forceinline__ void conv_item(const float* __restrict__ W, int K, int N, bf16* WT, const float* __restrict__ g, int mode, LAS float* scr, int item, int lane) {
;     ...
; #pragma unroll
;     for (int i = 0; i < 16; ++i) { const int kk = 4 * i + (lane >> 4); const float sc = g ? g[k0 + kk] : 1.f; LAS float* d = scr + kk * 65 + 4 * (lane & 15);
;         d[0] = v[i][0] * sc; d[1] = v[i][1] * sc; d[2] = v[i][2] * sc; d[3] = v[i][3] * sc; }
.LBB0_122:
	s_waitcnt vmcnt(0)
	v_pk_mul_f32 v[56:57], v[56:57], v[70:71] op_sel_hi:[1,0]
	v_add_u32_e32 v60, v65, v106
	ds_write2_b32 v60, v56, v57 offset1:1
	v_pk_mul_f32 v[56:57], v[58:59], v[70:71] op_sel_hi:[1,0]
	ds_write2_b32 v60, v56, v57 offset0:2 offset1:3
	s_and_b64 vcc, exec, s[4:5]
	v_add_u32_e32 v57, v65, v107
	s_cbranch_vccnz .LBB0_143
	s_ashr_i32 s3, s2, 31
	v_lshl_add_u64 v[58:59], s[2:3], 0, v[68:69]
	v_lshl_add_u64 v[58:59], v[58:59], 2, s[14:15]
	v_mov_b32_e32 v60, v136
	v_mov_b32_e32 v56, v137
	s_waitcnt vmcnt(1)
	v_pk_mul_f32 v[58:59], v[52:53], v[60:61] op_sel_hi:[1,0]
	v_pk_mul_f32 v[60:61], v[54:55], v[60:61] op_sel_hi:[1,0]
	ds_write2_b32 v57, v58, v59 offset1:1
	ds_write2_b32 v57, v60, v61 offset0:2 offset1:3
	s_cbranch_execnz .LBB0_125

; #define LAS __attribute__((address_space(3)))
; __device__ __forceinline__ void conv_item(const float* __restrict__ W, int K, int N, bf16* WT, const float* __restrict__ g, int mode, LAS float* scr, int item, int lane) {
;     ...
; #pragma unroll
;     for (int i = 0; i < 16; ++i) { const int kk = 4 * i + (lane >> 4); const float sc = g ? g[k0 + kk] : 1.f; LAS float* d = scr + kk * 65 + 4 * (lane & 15);
;         d[0] = v[i][0] * sc; d[1] = v[i][1] * sc; d[2] = v[i][2] * sc; d[3] = v[i][3] * sc; }
.LBB0_125:
	s_waitcnt vmcnt(0)
	v_pk_mul_f32 v[48:49], v[48:49], v[56:57] op_sel_hi:[1,0]
	v_add_u32_e32 v52, v65, v108
	ds_write2_b32 v52, v48, v49 offset1:1
	v_pk_mul_f32 v[48:49], v[50:51], v[56:57] op_sel_hi:[1,0]
	ds_write2_b32 v52, v48, v49 offset0:2 offset1:3
	s_and_b64 vcc, exec, s[4:5]
	v_add_u32_e32 v49, v65, v109
	s_cbranch_vccnz .LBB0_144
	s_ashr_i32 s3, s2, 31
	v_lshl_add_u64 v[50:51], s[2:3], 0, v[68:69]
	v_lshl_add_u64 v[50:51], v[50:51], 2, s[14:15]
	v_mov_b32_e32 v52, v138
	v_mov_b32_e32 v48, v139
	s_waitcnt vmcnt(1)
	v_pk_mul_f32 v[50:51], v[44:45], v[52:53] op_sel_hi:[1,0]
	v_pk_mul_f32 v[52:53], v[46:47], v[52:53] op_sel_hi:[1,0]
	ds_write2_b32 v49, v50, v51 offset1:1
	ds_write2_b32 v49, v52, v53 offset0:2 offset1:3
	s_cbranch_execnz .LBB0_128

; #define LAS __attribute__((address_space(3)))
; __device__ __forceinline__ void conv_item(const float* __restrict__ W, int K, int N, bf16* WT, const float* __restrict__ g, int mode, LAS float* scr, int item, int lane) {
;     ...
; #pragma unroll
;     for (int i = 0; i < 16; ++i) { const int kk = 4 * i + (lane >> 4); const float sc = g ? g[k0 + kk] : 1.f; LAS float* d = scr + kk * 65 + 4 * (lane & 15);
;         d[0] = v[i][0] * sc; d[1] = v[i][1] * sc; d[2] = v[i][2] * sc; d[3] = v[i][3] * sc; }
.LBB0_128:
	s_waitcnt vmcnt(0)
	v_pk_mul_f32 v[40:41], v[40:41], v[48:49] op_sel_hi:[1,0]
	v_add_u32_e32 v44, v65, v110
	ds_write2_b32 v44, v40, v41 offset1:1
	v_pk_mul_f32 v[40:41], v[42:43], v[48:49] op_sel_hi:[1,0]
	ds_write2_b32 v44, v40, v41 offset0:2 offset1:3
	s_and_b64 vcc, exec, s[4:5]
	v_add_u32_e32 v41, v65, v111
	s_cbranch_vccnz .LBB0_145
	s_ashr_i32 s3, s2, 31
	v_lshl_add_u64 v[42:43], s[2:3], 0, v[68:69]
	v_lshl_add_u64 v[42:43], v[42:43], 2, s[14:15]
	v_mov_b32_e32 v44, v140
	v_mov_b32_e32 v40, v141
	s_waitcnt vmcnt(1)
	v_pk_mul_f32 v[42:43], v[36:37], v[44:45] op_sel_hi:[1,0]
	v_pk_mul_f32 v[44:45], v[38:39], v[44:45] op_sel_hi:[1,0]
	ds_write2_b32 v41, v42, v43 offset1:1
	ds_write2_b32 v41, v44, v45 offset0:2 offset1:3
	s_cbranch_execnz .LBB0_131

; #define LAS __attribute__((address_space(3)))
; __device__ __forceinline__ void conv_item(const float* __restrict__ W, int K, int N, bf16* WT, const float* __restrict__ g, int mode, LAS float* scr, int item, int lane) {
;     ...
; #pragma unroll
;     for (int i = 0; i < 16; ++i) { const int kk = 4 * i + (lane >> 4); const float sc = g ? g[k0 + kk] : 1.f; LAS float* d = scr + kk * 65 + 4 * (lane & 15);
;         d[0] = v[i][0] * sc; d[1] = v[i][1] * sc; d[2] = v[i][2] * sc; d[3] = v[i][3] * sc; }
.LBB0_131:
	s_waitcnt vmcnt(0)
	v_pk_mul_f32 v[32:33], v[32:33], v[40:41] op_sel_hi:[1,0]
	v_add_u32_e32 v36, v65, v112
	ds_write2_b32 v36, v32, v33 offset1:1
	v_pk_mul_f32 v[32:33], v[34:35], v[40:41] op_sel_hi:[1,0]
	ds_write2_b32 v36, v32, v33 offset0:2 offset1:3
	s_and_b64 vcc, exec, s[4:5]
	v_add_u32_e32 v33, v65, v113
	s_cbranch_vccnz .LBB0_146
	s_ashr_i32 s3, s2, 31
	v_lshl_add_u64 v[34:35], s[2:3], 0, v[68:69]
	v_lshl_add_u64 v[34:35], v[34:35], 2, s[14:15]
	v_mov_b32_e32 v36, v142
	v_mov_b32_e32 v32, v143
	s_waitcnt vmcnt(1)
	v_pk_mul_f32 v[34:35], v[28:29], v[36:37] op_sel_hi:[1,0]
	v_pk_mul_f32 v[36:37], v[30:31], v[36:37] op_sel_hi:[1,0]
	ds_write2_b32 v33, v34, v35 offset1:1
	ds_write2_b32 v33, v36, v37 offset0:2 offset1:3
	s_cbranch_execnz .LBB0_134

; #define LAS __attribute__((address_space(3)))
; __device__ __forceinline__ void conv_item(const float* __restrict__ W, int K, int N, bf16* WT, const float* __restrict__ g, int mode, LAS float* scr, int item, int lane) {
;     ...
; #pragma unroll
;     for (int i = 0; i < 16; ++i) { const int kk = 4 * i + (lane >> 4); const float sc = g ? g[k0 + kk] : 1.f; LAS float* d = scr + kk * 65 + 4 * (lane & 15);
;         d[0] = v[i][0] * sc; d[1] = v[i][1] * sc; d[2] = v[i][2] * sc; d[3] = v[i][3] * sc; }
.LBB0_134:
	s_waitcnt vmcnt(0)
	v_pk_mul_f32 v[24:25], v[24:25], v[32:33] op_sel_hi:[1,0]
	v_add_u32_e32 v28, v65, v114
	ds_write2_b32 v28, v24, v25 offset1:1
	v_pk_mul_f32 v[24:25], v[26:27], v[32:33] op_sel_hi:[1,0]
	ds_write2_b32 v28, v24, v25 offset0:2 offset1:3
	s_and_b64 vcc, exec, s[4:5]
	v_add_u32_e32 v25, v65, v115
	s_cbranch_vccnz .LBB0_147
	s_ashr_i32 s3, s2, 31
	v_lshl_add_u64 v[26:27], s[2:3], 0, v[68:69]
	v_lshl_add_u64 v[26:27], v[26:27], 2, s[14:15]
	v_mov_b32_e32 v28, v144
	v_mov_b32_e32 v24, v145
	s_waitcnt vmcnt(1)
	v_pk_mul_f32 v[26:27], v[20:21], v[28:29] op_sel_hi:[1,0]
	v_pk_mul_f32 v[28:29], v[22:23], v[28:29] op_sel_hi:[1,0]
	ds_write2_b32 v25, v26, v27 offset1:1
	ds_write2_b32 v25, v28, v29 offset0:2 offset1:3
	s_cbranch_execnz .LBB0_137

; #define LAS __attribute__((address_space(3)))
; __device__ __forceinline__ void conv_item(const float* __restrict__ W, int K, int N, bf16* WT, const float* __restrict__ g, int mode, LAS float* scr, int item, int lane) {
;     ...
; #pragma unroll
;     for (int i = 0; i < 16; ++i) { const int kk = 4 * i + (lane >> 4); const float sc = g ? g[k0 + kk] : 1.f; LAS float* d = scr + kk * 65 + 4 * (lane & 15);
;         d[0] = v[i][0] * sc; d[1] = v[i][1] * sc; d[2] = v[i][2] * sc; d[3] = v[i][3] * sc; }
.LBB0_137:
	s_waitcnt vmcnt(0)
	v_pk_mul_f32 v[20:21], v[16:17], v[24:25] op_sel_hi:[1,0]
	v_add_u32_e32 v17, v65, v116
	v_pk_mul_f32 v[18:19], v[18:19], v[24:25] op_sel_hi:[1,0]
	ds_write2_b32 v17, v18, v19 offset0:2 offset1:3
	s_and_b64 vcc, exec, s[4:5]
	v_add_u32_e32 v18, 0x410, v17
	v_add_u32_e32 v19, 0x418, v17
	ds_write2_b32 v17, v20, v21 offset1:1
	s_cbranch_vccnz .LBB0_148
	s_ashr_i32 s3, s2, 31
	v_lshl_add_u64 v[20:21], s[2:3], 0, v[68:69]
	v_lshl_add_u64 v[20:21], v[20:21], 2, s[14:15]
	v_mov_b32_e32 v22, v146
	v_mov_b32_e32 v16, v147
	s_waitcnt vmcnt(1)
	v_pk_mul_f32 v[20:21], v[12:13], v[22:23] op_sel_hi:[1,0]
	v_pk_mul_f32 v[22:23], v[14:15], v[22:23] op_sel_hi:[1,0]
	ds_write2_b32 v18, v20, v21 offset1:1
	ds_write2_b32 v19, v22, v23 offset1:1
	s_cbranch_execnz .LBB0_140

; #define LAS __attribute__((address_space(3)))
; __device__ __forceinline__ void conv_item(const float* __restrict__ W, int K, int N, bf16* WT, const float* __restrict__ g, int mode, LAS float* scr, int item, int lane) {
;     ...
; #pragma unroll
;     for (int i = 0; i < 16; ++i) { const int kk = 4 * i + (lane >> 4); const float sc = g ? g[k0 + kk] : 1.f; LAS float* d = scr + kk * 65 + 4 * (lane & 15);
;         d[0] = v[i][0] * sc; d[1] = v[i][1] * sc; d[2] = v[i][2] * sc; d[3] = v[i][3] * sc; }
.LBB0_140:
	s_waitcnt vmcnt(0)
	v_pk_mul_f32 v[8:9], v[8:9], v[16:17] op_sel_hi:[1,0]
	v_add_u32_e32 v12, 0x820, v17
	ds_write2_b32 v12, v8, v9 offset1:1
	v_pk_mul_f32 v[8:9], v[10:11], v[16:17] op_sel_hi:[1,0]
	v_add_u32_e32 v10, 0x828, v17
	ds_write2_b32 v10, v8, v9 offset1:1
	s_and_b64 vcc, exec, s[4:5]
	v_add_u32_e32 v9, 0xc30, v17
	v_add_u32_e32 v10, 0xc38, v17
	s_cbranch_vccnz .LBB0_149
	s_ashr_i32 s3, s2, 31
	v_lshl_add_u64 v[12:13], s[2:3], 0, v[68:69]
	v_lshl_add_u64 v[12:13], v[12:13], 2, s[14:15]
	v_mov_b32_e32 v14, v148
	v_mov_b32_e32 v8, v149
	s_waitcnt vmcnt(1)
	v_pk_mul_f32 v[12:13], v[4:5], v[14:15] op_sel_hi:[1,0]
	v_pk_mul_f32 v[14:15], v[6:7], v[14:15] op_sel_hi:[1,0]
	ds_write2_b32 v9, v12, v13 offset1:1
	ds_write2_b32 v10, v14, v15 offset1:1
	s_cbranch_execnz .LBB0_50
	s_branch .LBB0_49
